# G1/G4: first two lines of the next tile's weight rows touched into L2 at the start of the current tile's epilogue
# baseline (speedup 1.0000x reference)
.LBB0_178:
	s_add_u32 s94, s92, 0x3ff800
	s_addc_u32 s95, s93, 0
	s_or_b64 exec, exec, s[20:21]
	v_mul_f32_e32 v124, 0xbfb8aa3b, v158
	v_mul_f32_e32 v128, 0xbfb8aa3b, v118
	v_exp_f32_e32 v124, v124
	v_exp_f32_e32 v128, v128
	s_movk_i32 s19, 0x4400
	v_mul_lo_u32 v122, v197, s19
	v_add_f32_e32 v124, 1.0, v124
	v_add_f32_e32 v128, 1.0, v128
	v_rcp_f32_e32 v124, v124
	v_rcp_f32_e32 v128, v128
	v_lshl_or_b32 v123, v199, 2, v122
	s_movk_i32 s19, 0x440
	v_mul_f32_e32 v124, v158, v124
	v_mul_f32_e32 v118, v118, v128
	v_mul_f32_e32 v124, v124, v154
	v_mad_u32_u24 v123, v196, s19, v123
	v_mul_f32_e32 v114, v118, v114
	s_waitcnt vmcnt(0) lgkmcnt(0)
	s_barrier
	global_load_dword v231, v190, s[94:95]
	global_load_dword v231, v190, s[94:95] offset:128
	global_load_dword v231, v192, s[94:95]
	global_load_dword v231, v192, s[94:95] offset:128
	v_mul_f32_e32 v125, 0xbfb8aa3b, v159
	ds_write2_b32 v123, v124, v114 offset1:16
	v_mul_f32_e32 v114, 0xbfb8aa3b, v119
	v_exp_f32_e32 v125, v125
	v_exp_f32_e32 v114, v114
	v_mul_f32_e32 v126, 0xbfb8aa3b, v160
	v_exp_f32_e32 v126, v126
	v_add_f32_e32 v125, 1.0, v125
	v_add_f32_e32 v114, 1.0, v114
	v_rcp_f32_e32 v125, v125
	v_rcp_f32_e32 v114, v114
	v_add_f32_e32 v126, 1.0, v126
	v_rcp_f32_e32 v126, v126
	v_mul_f32_e32 v125, v159, v125
	v_mul_f32_e32 v114, v119, v114
	v_mul_f32_e32 v125, v125, v155
	v_mul_f32_e32 v114, v114, v115
	ds_write2_b32 v123, v125, v114 offset0:68 offset1:84
	v_mul_f32_e32 v114, 0xbfb8aa3b, v120
	v_exp_f32_e32 v114, v114
	v_mul_f32_e32 v126, v160, v126
	v_mul_f32_e32 v126, v126, v156
	v_mul_f32_e32 v127, 0xbfb8aa3b, v161
	v_add_f32_e32 v114, 1.0, v114
	v_rcp_f32_e32 v114, v114
	v_exp_f32_e32 v127, v127
	v_readlane_b32 s22, v254, 46
	v_mul_f32_e32 v114, v120, v114
	v_mul_f32_e32 v114, v114, v116
	ds_write2_b32 v123, v126, v114 offset0:136 offset1:152
	v_mul_f32_e32 v114, 0xbfb8aa3b, v121
	v_exp_f32_e32 v114, v114
	v_add_f32_e32 v127, 1.0, v127
	v_rcp_f32_e32 v127, v127
	v_add_f32_e32 v114, 1.0, v114
	v_rcp_f32_e32 v114, v114
	v_mul_f32_e32 v127, v161, v127
	v_mul_f32_e32 v127, v127, v157
	v_mul_f32_e32 v114, v121, v114
	v_mul_f32_e32 v114, v114, v117
	ds_write2_b32 v123, v127, v114 offset0:204 offset1:220
	v_mul_f32_e32 v114, 0xbfb8aa3b, v110
	v_exp_f32_e32 v114, v114
	s_nop 0
	v_add_f32_e32 v114, 1.0, v114
	v_rcp_f32_e32 v114, v114
	s_nop 0
	v_mul_f32_e32 v110, v110, v114
	v_mul_f32_e32 v106, v110, v106
	v_mul_f32_e32 v110, 0xbfb8aa3b, v111
	v_exp_f32_e32 v110, v110
	s_nop 0
	v_add_f32_e32 v110, 1.0, v110
	v_rcp_f32_e32 v110, v110
	s_nop 0
	v_mul_f32_e32 v110, v111, v110
	v_mul_f32_e32 v107, v110, v107
	v_mul_f32_e32 v110, 0xbfb8aa3b, v112
	v_exp_f32_e32 v110, v110
	s_nop 0
	v_add_f32_e32 v110, 1.0, v110
	v_rcp_f32_e32 v110, v110
	s_nop 0
	v_mul_f32_e32 v110, v112, v110
	v_mul_f32_e32 v108, v110, v108
	v_mul_f32_e32 v110, 0xbfb8aa3b, v113
	v_exp_f32_e32 v110, v110
	s_nop 0
	v_add_f32_e32 v110, 1.0, v110
	v_rcp_f32_e32 v110, v110
	s_nop 0
	v_mul_f32_e32 v110, v113, v110
	v_mul_f32_e32 v109, v110, v109
	v_mul_f32_e32 v110, 0xbfb8aa3b, v102
	v_exp_f32_e32 v110, v110
	s_nop 0
	v_add_f32_e32 v110, 1.0, v110
	v_rcp_f32_e32 v110, v110
	s_nop 0
	v_mul_f32_e32 v102, v102, v110
	v_mul_f32_e32 v98, v102, v98
	ds_write2_b32 v123, v106, v98 offset0:32 offset1:48
	v_mul_f32_e32 v98, 0xbfb8aa3b, v103
	v_exp_f32_e32 v98, v98
	s_nop 0
	v_add_f32_e32 v98, 1.0, v98
	v_rcp_f32_e32 v98, v98
	s_nop 0
	v_mul_f32_e32 v98, v103, v98
	v_mul_f32_e32 v98, v98, v99
	ds_write2_b32 v123, v107, v98 offset0:100 offset1:116
	v_mul_f32_e32 v98, 0xbfb8aa3b, v104
	v_exp_f32_e32 v98, v98
	s_nop 0
	v_add_f32_e32 v98, 1.0, v98
	v_rcp_f32_e32 v98, v98
	s_nop 0
	v_mul_f32_e32 v98, v104, v98
	v_mul_f32_e32 v98, v98, v100
	ds_write2_b32 v123, v108, v98 offset0:168 offset1:184
	v_mul_f32_e32 v98, 0xbfb8aa3b, v105
	v_exp_f32_e32 v98, v98
	s_nop 0
	v_add_f32_e32 v98, 1.0, v98
	v_rcp_f32_e32 v98, v98
	s_nop 0
	v_mul_f32_e32 v98, v105, v98
	v_mul_f32_e32 v98, v98, v101
	ds_write2_b32 v123, v109, v98 offset0:236 offset1:252
	v_mul_f32_e32 v98, 0xbfb8aa3b, v94
	v_exp_f32_e32 v98, v98
	s_nop 0
	v_add_f32_e32 v98, 1.0, v98
	v_rcp_f32_e32 v98, v98
	s_nop 0
	v_mul_f32_e32 v94, v94, v98
	v_mul_f32_e32 v90, v94, v90
	v_mul_f32_e32 v94, 0xbfb8aa3b, v95
	v_exp_f32_e32 v94, v94
	s_nop 0
	v_add_f32_e32 v94, 1.0, v94
	v_rcp_f32_e32 v94, v94
	s_nop 0
	v_mul_f32_e32 v94, v95, v94
	v_mul_f32_e32 v91, v94, v91
	v_mul_f32_e32 v94, 0xbfb8aa3b, v96
	v_exp_f32_e32 v94, v94
	s_nop 0
	v_add_f32_e32 v94, 1.0, v94
	v_rcp_f32_e32 v94, v94
	s_nop 0
	v_mul_f32_e32 v94, v96, v94
	v_mul_f32_e32 v92, v94, v92
	v_mul_f32_e32 v94, 0xbfb8aa3b, v97
	v_exp_f32_e32 v94, v94
	s_nop 0
	v_add_f32_e32 v94, 1.0, v94
	v_rcp_f32_e32 v94, v94
	s_nop 0
	v_mul_f32_e32 v94, v97, v94
	v_mul_f32_e32 v93, v94, v93
	v_mul_f32_e32 v94, 0xbfb8aa3b, v86
	v_exp_f32_e32 v94, v94
	s_nop 0
	v_add_f32_e32 v94, 1.0, v94
	v_rcp_f32_e32 v94, v94
	s_nop 0
	v_mul_f32_e32 v86, v86, v94
	v_mul_f32_e32 v82, v86, v82
	v_add_u32_e32 v86, 0x1000, v123
	ds_write2_b32 v86, v90, v82 offset0:64 offset1:80
	v_mul_f32_e32 v82, 0xbfb8aa3b, v87
	v_exp_f32_e32 v82, v82
	s_nop 0
	v_add_f32_e32 v82, 1.0, v82
	v_rcp_f32_e32 v82, v82
	s_nop 0
	v_mul_f32_e32 v82, v87, v82
	v_mul_f32_e32 v82, v82, v83
	ds_write2_b32 v86, v91, v82 offset0:132 offset1:148
	v_mul_f32_e32 v82, 0xbfb8aa3b, v88
	v_exp_f32_e32 v82, v82
	v_add_u32_e32 v83, 0x1400, v123
	v_add_f32_e32 v82, 1.0, v82
	v_rcp_f32_e32 v82, v82
	s_nop 0
	v_mul_f32_e32 v82, v88, v82
	v_mul_f32_e32 v82, v82, v84
	ds_write2_b32 v86, v92, v82 offset0:200 offset1:216
	v_mul_f32_e32 v82, 0xbfb8aa3b, v89
	v_exp_f32_e32 v82, v82
	s_nop 0
	v_add_f32_e32 v82, 1.0, v82
	v_rcp_f32_e32 v82, v82
	s_nop 0
	v_mul_f32_e32 v82, v89, v82
	v_mul_f32_e32 v82, v82, v85
	ds_write2_b32 v83, v93, v82 offset0:12 offset1:28
	v_mul_f32_e32 v82, 0xbfb8aa3b, v78
	v_exp_f32_e32 v82, v82
	s_nop 0
	v_add_f32_e32 v82, 1.0, v82
	v_rcp_f32_e32 v82, v82
	s_nop 0
	v_mul_f32_e32 v78, v78, v82
	v_mul_f32_e32 v74, v78, v74
	v_mul_f32_e32 v78, 0xbfb8aa3b, v79
	v_exp_f32_e32 v78, v78
	s_nop 0
	v_add_f32_e32 v78, 1.0, v78
	v_rcp_f32_e32 v78, v78
	s_nop 0
	v_mul_f32_e32 v78, v79, v78
	v_mul_f32_e32 v75, v78, v75
	v_mul_f32_e32 v78, 0xbfb8aa3b, v80
	v_exp_f32_e32 v78, v78
	s_nop 0
	v_add_f32_e32 v78, 1.0, v78
	v_rcp_f32_e32 v78, v78
	s_nop 0
	v_mul_f32_e32 v78, v80, v78
	v_mul_f32_e32 v76, v78, v76
	v_mul_f32_e32 v78, 0xbfb8aa3b, v81
	v_exp_f32_e32 v78, v78
	s_nop 0
	v_add_f32_e32 v78, 1.0, v78
	v_rcp_f32_e32 v78, v78
	s_nop 0
	v_mul_f32_e32 v78, v81, v78
	v_mul_f32_e32 v77, v78, v77
	v_mul_f32_e32 v78, 0xbfb8aa3b, v70
	v_exp_f32_e32 v78, v78
	s_nop 0
	v_add_f32_e32 v78, 1.0, v78
	v_rcp_f32_e32 v78, v78
	s_nop 0
	v_mul_f32_e32 v70, v70, v78
	v_mul_f32_e32 v66, v70, v66
	ds_write2_b32 v86, v74, v66 offset0:96 offset1:112
	v_mul_f32_e32 v66, 0xbfb8aa3b, v71
	v_exp_f32_e32 v66, v66
	s_nop 0
	v_add_f32_e32 v66, 1.0, v66
	v_rcp_f32_e32 v66, v66
	s_nop 0
	v_mul_f32_e32 v66, v71, v66
	v_mul_f32_e32 v66, v66, v67
	ds_write2_b32 v86, v75, v66 offset0:164 offset1:180
	v_mul_f32_e32 v66, 0xbfb8aa3b, v72
	v_exp_f32_e32 v66, v66
	s_nop 0
	v_add_f32_e32 v66, 1.0, v66
	v_rcp_f32_e32 v66, v66
	s_nop 0
	v_mul_f32_e32 v66, v72, v66
	v_mul_f32_e32 v66, v66, v68
	ds_write2_b32 v86, v76, v66 offset0:232 offset1:248
	v_mul_f32_e32 v66, 0xbfb8aa3b, v73
	v_exp_f32_e32 v66, v66
	s_nop 0
	v_add_f32_e32 v66, 1.0, v66
	v_rcp_f32_e32 v66, v66
	s_nop 0
	v_mul_f32_e32 v66, v73, v66
	v_mul_f32_e32 v66, v66, v69
	ds_write2_b32 v83, v77, v66 offset0:44 offset1:60
	v_mul_f32_e32 v66, 0xbfb8aa3b, v62
	v_exp_f32_e32 v66, v66
	s_nop 0
	v_add_f32_e32 v66, 1.0, v66
	v_rcp_f32_e32 v66, v66
	s_nop 0
	v_mul_f32_e32 v62, v62, v66
	v_mul_f32_e32 v58, v62, v58
	v_mul_f32_e32 v62, 0xbfb8aa3b, v63
	v_exp_f32_e32 v62, v62
	s_nop 0
	v_add_f32_e32 v62, 1.0, v62
	v_rcp_f32_e32 v62, v62
	s_nop 0
	v_mul_f32_e32 v62, v63, v62
	v_mul_f32_e32 v59, v62, v59
	v_mul_f32_e32 v62, 0xbfb8aa3b, v64
	v_exp_f32_e32 v62, v62
	s_nop 0
	v_add_f32_e32 v62, 1.0, v62
	v_rcp_f32_e32 v62, v62
	s_nop 0
	v_mul_f32_e32 v62, v64, v62
	v_mul_f32_e32 v60, v62, v60
	v_mul_f32_e32 v62, 0xbfb8aa3b, v65
	v_exp_f32_e32 v62, v62
	s_nop 0
	v_add_f32_e32 v62, 1.0, v62
	v_rcp_f32_e32 v62, v62
	s_nop 0
	v_mul_f32_e32 v62, v65, v62
	v_mul_f32_e32 v61, v62, v61
	v_mul_f32_e32 v62, 0xbfb8aa3b, v54
	v_exp_f32_e32 v62, v62
	s_nop 0
	v_add_f32_e32 v62, 1.0, v62
	v_rcp_f32_e32 v62, v62
	s_nop 0
	v_mul_f32_e32 v54, v54, v62
	v_mul_f32_e32 v50, v54, v50
	v_add_u32_e32 v54, 0x2000, v123
	ds_write2_b32 v54, v58, v50 offset0:128 offset1:144
	v_mul_f32_e32 v50, 0xbfb8aa3b, v55
	v_exp_f32_e32 v50, v50
	s_nop 0
	v_add_f32_e32 v50, 1.0, v50
	v_rcp_f32_e32 v50, v50
	s_nop 0
	v_mul_f32_e32 v50, v55, v50
	v_mul_f32_e32 v50, v50, v51
	ds_write2_b32 v54, v59, v50 offset0:196 offset1:212
	v_mul_f32_e32 v50, 0xbfb8aa3b, v56
	v_exp_f32_e32 v50, v50
	v_add_u32_e32 v51, 0x2400, v123
	v_add_f32_e32 v50, 1.0, v50
	v_rcp_f32_e32 v50, v50
	s_nop 0
	v_mul_f32_e32 v50, v56, v50
	v_mul_f32_e32 v50, v50, v52
	ds_write2_b32 v51, v60, v50 offset0:8 offset1:24
	v_mul_f32_e32 v50, 0xbfb8aa3b, v57
	v_exp_f32_e32 v50, v50
	s_nop 0
	v_add_f32_e32 v50, 1.0, v50
	v_rcp_f32_e32 v50, v50
	s_nop 0
	v_mul_f32_e32 v50, v57, v50
	v_mul_f32_e32 v50, v50, v53
	ds_write2_b32 v51, v61, v50 offset0:76 offset1:92
	v_mul_f32_e32 v50, 0xbfb8aa3b, v46
	v_exp_f32_e32 v50, v50
	s_nop 0
	v_add_f32_e32 v50, 1.0, v50
	v_rcp_f32_e32 v50, v50
	s_nop 0
	v_mul_f32_e32 v46, v46, v50
	v_mul_f32_e32 v42, v46, v42
	v_mul_f32_e32 v46, 0xbfb8aa3b, v47
	v_exp_f32_e32 v46, v46
	s_nop 0
	v_add_f32_e32 v46, 1.0, v46
	v_rcp_f32_e32 v46, v46
	s_nop 0
	v_mul_f32_e32 v46, v47, v46
	v_mul_f32_e32 v43, v46, v43
	v_mul_f32_e32 v46, 0xbfb8aa3b, v48
	v_exp_f32_e32 v46, v46
	s_nop 0
	v_add_f32_e32 v46, 1.0, v46
	v_rcp_f32_e32 v46, v46
	s_nop 0
	v_mul_f32_e32 v46, v48, v46
	v_mul_f32_e32 v44, v46, v44
	v_mul_f32_e32 v46, 0xbfb8aa3b, v49
	v_exp_f32_e32 v46, v46
	s_nop 0
	v_add_f32_e32 v46, 1.0, v46
	v_rcp_f32_e32 v46, v46
	s_nop 0
	v_mul_f32_e32 v46, v49, v46
	v_mul_f32_e32 v45, v46, v45
	v_mul_f32_e32 v46, 0xbfb8aa3b, v38
	v_exp_f32_e32 v46, v46
	s_nop 0
	v_add_f32_e32 v46, 1.0, v46
	v_rcp_f32_e32 v46, v46
	s_nop 0
	v_mul_f32_e32 v38, v38, v46
	v_mul_f32_e32 v34, v38, v34
	ds_write2_b32 v54, v42, v34 offset0:160 offset1:176
	v_mul_f32_e32 v34, 0xbfb8aa3b, v39
	v_exp_f32_e32 v34, v34
	s_nop 0
	v_add_f32_e32 v34, 1.0, v34
	v_rcp_f32_e32 v34, v34
	s_nop 0
	v_mul_f32_e32 v34, v39, v34
	v_mul_f32_e32 v34, v34, v35
	ds_write2_b32 v54, v43, v34 offset0:228 offset1:244
	v_mul_f32_e32 v34, 0xbfb8aa3b, v40
	v_exp_f32_e32 v34, v34
	s_nop 0
	v_add_f32_e32 v34, 1.0, v34
	v_rcp_f32_e32 v34, v34
	s_nop 0
	v_mul_f32_e32 v34, v40, v34
	v_mul_f32_e32 v34, v34, v36
	ds_write2_b32 v51, v44, v34 offset0:40 offset1:56
	v_mul_f32_e32 v34, 0xbfb8aa3b, v41
	v_exp_f32_e32 v34, v34
	s_nop 0
	v_add_f32_e32 v34, 1.0, v34
	v_rcp_f32_e32 v34, v34
	s_nop 0
	v_mul_f32_e32 v34, v41, v34
	v_mul_f32_e32 v34, v34, v37
	ds_write2_b32 v51, v45, v34 offset0:108 offset1:124
	v_mul_f32_e32 v34, 0xbfb8aa3b, v30
	v_exp_f32_e32 v34, v34
	s_nop 0
	v_add_f32_e32 v34, 1.0, v34
	v_rcp_f32_e32 v34, v34
	s_nop 0
	v_mul_f32_e32 v30, v30, v34
	v_mul_f32_e32 v26, v30, v26
	v_mul_f32_e32 v30, 0xbfb8aa3b, v31
	v_exp_f32_e32 v30, v30
	s_nop 0
	v_add_f32_e32 v30, 1.0, v30
	v_rcp_f32_e32 v30, v30
	s_nop 0
	v_mul_f32_e32 v30, v31, v30
	v_mul_f32_e32 v27, v30, v27
	v_mul_f32_e32 v30, 0xbfb8aa3b, v32
	v_exp_f32_e32 v30, v30
	s_nop 0
	v_add_f32_e32 v30, 1.0, v30
	v_rcp_f32_e32 v30, v30
	s_nop 0
	v_mul_f32_e32 v30, v32, v30
	v_mul_f32_e32 v28, v30, v28
	v_mul_f32_e32 v30, 0xbfb8aa3b, v33
	v_exp_f32_e32 v30, v30
	s_nop 0
	v_add_f32_e32 v30, 1.0, v30
	v_rcp_f32_e32 v30, v30
	s_nop 0
	v_mul_f32_e32 v30, v33, v30
	v_mul_f32_e32 v29, v30, v29
	v_mul_f32_e32 v30, 0xbfb8aa3b, v22
	v_exp_f32_e32 v30, v30
	s_nop 0
	v_add_f32_e32 v30, 1.0, v30
	v_rcp_f32_e32 v30, v30
	s_nop 0
	v_mul_f32_e32 v22, v22, v30
	v_mul_f32_e32 v18, v22, v18
	v_add_u32_e32 v22, 0x3000, v123
	ds_write2_b32 v22, v26, v18 offset0:192 offset1:208
	v_mul_f32_e32 v18, 0xbfb8aa3b, v23
	v_exp_f32_e32 v18, v18
	s_nop 0
	v_add_f32_e32 v18, 1.0, v18
	v_rcp_f32_e32 v18, v18
	s_nop 0
	v_mul_f32_e32 v18, v23, v18
	v_mul_f32_e32 v18, v18, v19
	v_add_u32_e32 v19, 0x3400, v123
	ds_write2_b32 v19, v27, v18 offset0:4 offset1:20
	v_mul_f32_e32 v18, 0xbfb8aa3b, v24
	v_exp_f32_e32 v18, v18
	s_nop 0
	v_add_f32_e32 v18, 1.0, v18
	v_rcp_f32_e32 v18, v18
	s_nop 0
	v_mul_f32_e32 v18, v24, v18
	v_mul_f32_e32 v18, v18, v20
	ds_write2_b32 v19, v28, v18 offset0:72 offset1:88
	v_mul_f32_e32 v18, 0xbfb8aa3b, v25
	v_exp_f32_e32 v18, v18
	s_nop 0
	v_add_f32_e32 v18, 1.0, v18
	v_rcp_f32_e32 v18, v18
	s_nop 0
	v_mul_f32_e32 v18, v25, v18
	v_mul_f32_e32 v18, v18, v21
	ds_write2_b32 v19, v29, v18 offset0:140 offset1:156
	v_mul_f32_e32 v18, 0xbfb8aa3b, v14
	v_exp_f32_e32 v18, v18
	s_nop 0
	v_add_f32_e32 v18, 1.0, v18
	v_rcp_f32_e32 v18, v18
	s_nop 0
	v_mul_f32_e32 v14, v14, v18
	v_mul_f32_e32 v10, v14, v10
	v_mul_f32_e32 v14, 0xbfb8aa3b, v15
	v_exp_f32_e32 v14, v14
	s_nop 0
	v_add_f32_e32 v14, 1.0, v14
	v_rcp_f32_e32 v14, v14
	s_nop 0
	v_mul_f32_e32 v14, v15, v14
	v_mul_f32_e32 v11, v14, v11
	v_mul_f32_e32 v14, 0xbfb8aa3b, v16
	v_exp_f32_e32 v14, v14
	s_nop 0
	v_add_f32_e32 v14, 1.0, v14
	v_rcp_f32_e32 v14, v14
	s_nop 0
	v_mul_f32_e32 v14, v16, v14
	v_mul_f32_e32 v12, v14, v12
	v_mul_f32_e32 v14, 0xbfb8aa3b, v17
	v_exp_f32_e32 v14, v14
	s_nop 0
	v_add_f32_e32 v14, 1.0, v14
	v_rcp_f32_e32 v14, v14
	s_nop 0
	v_mul_f32_e32 v14, v17, v14
	v_mul_f32_e32 v13, v14, v13
	v_mul_f32_e32 v14, 0xbfb8aa3b, v6
	v_exp_f32_e32 v14, v14
	s_nop 0
	v_add_f32_e32 v14, 1.0, v14
	v_rcp_f32_e32 v14, v14
	s_nop 0
	v_mul_f32_e32 v6, v6, v14
	v_mul_f32_e32 v2, v6, v2
	ds_write2_b32 v22, v10, v2 offset0:224 offset1:240
	v_mul_f32_e32 v2, 0xbfb8aa3b, v7
	v_exp_f32_e32 v2, v2
	s_nop 0
	v_add_f32_e32 v2, 1.0, v2
	v_rcp_f32_e32 v2, v2
	s_nop 0
	v_mul_f32_e32 v2, v7, v2
	v_mul_f32_e32 v2, v2, v3
	ds_write2_b32 v19, v11, v2 offset0:36 offset1:52
	v_mul_f32_e32 v2, 0xbfb8aa3b, v8
	v_exp_f32_e32 v2, v2
	s_nop 0
	v_add_f32_e32 v2, 1.0, v2
	v_rcp_f32_e32 v2, v2
	s_nop 0
	v_mul_f32_e32 v2, v8, v2
	v_mul_f32_e32 v2, v2, v4
	ds_write2_b32 v19, v12, v2 offset0:104 offset1:120
	v_mul_f32_e32 v2, 0xbfb8aa3b, v9
	v_exp_f32_e32 v2, v2
	v_lshl_add_u32 v12, v0, 6, s22
	v_lshl_or_b32 v0, v195, 7, s17
	v_lshlrev_b32_e32 v4, 3, v194
	v_add_f32_e32 v2, 1.0, v2
	v_rcp_f32_e32 v2, v2
	s_add_i32 s17, s8, 32
	s_cmp_gt_u32 s8, 55
	s_mov_b32 s8, s17
	v_mul_f32_e32 v2, v9, v2
	v_mul_f32_e32 v2, v2, v5
	ds_write2_b32 v19, v13, v2 offset0:172 offset1:188
	v_lshl_add_u64 v[2:3], s[46:47], 0, v[0:1]
	v_lshrrev_b32_e32 v0, 3, v194
	v_and_b32_e32 v13, 56, v4
	v_mul_u32_u24_e32 v4, 0x110, v0
	v_lshlrev_b32_e32 v5, 2, v13
	v_add3_u32 v14, v122, v4, v5
	ds_read_b128 v[4:7], v14
	ds_read_b128 v[8:11], v14 offset:16
	v_or_b32_e32 v12, v12, v0
	v_lshlrev_b32_e32 v0, 1, v13
	s_waitcnt lgkmcnt(1)
	v_cvt_pk_bf16_f32 v4, v4, v5
	v_cvt_pk_bf16_f32 v5, v6, v7
	s_waitcnt lgkmcnt(0)
	v_cvt_pk_bf16_f32 v6, v8, v9
	v_mad_i64_i32 v[8:9], s[20:21], v12, s5, v[2:3]
	v_cvt_pk_bf16_f32 v7, v10, v11
	v_lshl_add_u64 v[8:9], v[8:9], 0, v[0:1]
	global_store_dwordx4 v[8:9], v[4:7], off
	ds_read_b128 v[4:7], v14 offset:2176
	ds_read_b128 v[8:11], v14 offset:2192
	s_waitcnt lgkmcnt(1)
	v_cvt_pk_bf16_f32 v4, v4, v5
	v_cvt_pk_bf16_f32 v5, v6, v7
	s_waitcnt lgkmcnt(0)
	v_cvt_pk_bf16_f32 v6, v8, v9
	v_or_b32_e32 v8, 8, v12
	v_mad_i64_i32 v[8:9], s[20:21], v8, s5, v[2:3]
	v_cvt_pk_bf16_f32 v7, v10, v11
	v_lshl_add_u64 v[8:9], v[8:9], 0, v[0:1]
	global_store_dwordx4 v[8:9], v[4:7], off
	ds_read_b128 v[4:7], v14 offset:4352
	ds_read_b128 v[8:11], v14 offset:4368
	s_waitcnt lgkmcnt(1)
	v_cvt_pk_bf16_f32 v4, v4, v5
	v_cvt_pk_bf16_f32 v5, v6, v7
	s_waitcnt lgkmcnt(0)
	v_cvt_pk_bf16_f32 v6, v8, v9
	v_or_b32_e32 v8, 16, v12
	v_mad_i64_i32 v[8:9], s[20:21], v8, s5, v[2:3]
	v_cvt_pk_bf16_f32 v7, v10, v11
	v_lshl_add_u64 v[8:9], v[8:9], 0, v[0:1]
	global_store_dwordx4 v[8:9], v[4:7], off
	ds_read_b128 v[4:7], v14 offset:6528
	ds_read_b128 v[8:11], v14 offset:6544
	s_waitcnt lgkmcnt(1)
	v_cvt_pk_bf16_f32 v4, v4, v5
	v_cvt_pk_bf16_f32 v5, v6, v7
	s_waitcnt lgkmcnt(0)
	v_cvt_pk_bf16_f32 v6, v8, v9
	v_or_b32_e32 v8, 24, v12
	v_mad_i64_i32 v[8:9], s[20:21], v8, s5, v[2:3]
	v_cvt_pk_bf16_f32 v7, v10, v11
	v_lshl_add_u64 v[8:9], v[8:9], 0, v[0:1]
	global_store_dwordx4 v[8:9], v[4:7], off
	ds_read_b128 v[4:7], v14 offset:8704
	ds_read_b128 v[8:11], v14 offset:8720
	s_waitcnt lgkmcnt(1)
	v_cvt_pk_bf16_f32 v4, v4, v5
	v_cvt_pk_bf16_f32 v5, v6, v7
	s_waitcnt lgkmcnt(0)
	v_cvt_pk_bf16_f32 v6, v8, v9
	v_or_b32_e32 v8, 32, v12
	v_mad_i64_i32 v[8:9], s[20:21], v8, s5, v[2:3]
	v_cvt_pk_bf16_f32 v7, v10, v11
	v_lshl_add_u64 v[8:9], v[8:9], 0, v[0:1]
	global_store_dwordx4 v[8:9], v[4:7], off
	ds_read_b128 v[4:7], v14 offset:10880
	ds_read_b128 v[8:11], v14 offset:10896
	s_waitcnt lgkmcnt(1)
	v_cvt_pk_bf16_f32 v4, v4, v5
	v_cvt_pk_bf16_f32 v5, v6, v7
	s_waitcnt lgkmcnt(0)
	v_cvt_pk_bf16_f32 v6, v8, v9
	v_or_b32_e32 v8, 40, v12
	v_mad_i64_i32 v[8:9], s[20:21], v8, s5, v[2:3]
	v_cvt_pk_bf16_f32 v7, v10, v11
	v_lshl_add_u64 v[8:9], v[8:9], 0, v[0:1]
	global_store_dwordx4 v[8:9], v[4:7], off
	ds_read_b128 v[4:7], v14 offset:13056
	ds_read_b128 v[8:11], v14 offset:13072
	s_waitcnt lgkmcnt(1)
	v_cvt_pk_bf16_f32 v4, v4, v5
	v_cvt_pk_bf16_f32 v5, v6, v7
	s_waitcnt lgkmcnt(0)
	v_cvt_pk_bf16_f32 v6, v8, v9
	v_or_b32_e32 v8, 48, v12
	v_mad_i64_i32 v[8:9], s[20:21], v8, s5, v[2:3]
	v_cvt_pk_bf16_f32 v7, v10, v11
	v_lshl_add_u64 v[8:9], v[8:9], 0, v[0:1]
	global_store_dwordx4 v[8:9], v[4:7], off
	ds_read_b128 v[4:7], v14 offset:15232
	ds_read_b128 v[8:11], v14 offset:15248
	s_waitcnt lgkmcnt(1)
	v_cvt_pk_bf16_f32 v4, v4, v5
	v_cvt_pk_bf16_f32 v5, v6, v7
	s_waitcnt lgkmcnt(0)
	v_cvt_pk_bf16_f32 v6, v8, v9
	v_or_b32_e32 v8, 56, v12
	v_mad_i64_i32 v[2:3], s[20:21], v8, s5, v[2:3]
	v_cvt_pk_bf16_f32 v7, v10, v11
	v_lshl_add_u64 v[2:3], v[2:3], 0, v[0:1]
	global_store_dwordx4 v[2:3], v[4:7], off
	s_cbranch_scc1 .LBB0_167

.LBB0_661:
	s_add_u32 s36, s42, 0x3ff800
	s_addc_u32 s37, s43, 0
	s_or_b64 exec, exec, s[20:21]
	v_lshlrev_b32_e32 v167, 6, v230
	v_readlane_b32 s20, v254, 46
	v_lshl_or_b32 v164, v201, 7, s19
	s_cmpk_lt_u32 s19, 0xc00
	v_add_u32_e32 v165, s20, v167
	s_mov_b64 s[20:21], -1
	s_waitcnt vmcnt(0) lgkmcnt(0)
	s_barrier
	global_load_dword v231, v192, s[36:37]
	global_load_dword v231, v192, s[36:37] offset:128
	global_load_dword v231, v194, s[36:37]
	global_load_dword v231, v194, s[36:37] offset:128
	s_cbranch_scc0 .LBB0_678
	s_movk_i32 s20, 0x4400
	v_mul_lo_u32 v166, v187, s20
	v_lshl_or_b32 v0, v199, 2, v166
	s_movk_i32 s20, 0x440
	v_mad_u32_u24 v173, v197, s20, v0
	v_add_u32_e32 v174, 0x1000, v173
	v_add_u32_e32 v175, 0x1400, v173
	v_add_u32_e32 v176, 0x2000, v173
	v_add_u32_e32 v177, 0x2400, v173
	v_add_u32_e32 v179, 0x3000, v173
	v_add_u32_e32 v178, 0x3400, v173
	s_cmpk_lt_u32 s19, 0x200
	ds_write2_b32 v173, v126, v122 offset1:16
	ds_write2_b32 v173, v127, v123 offset0:68 offset1:84
	ds_write2_b32 v173, v128, v124 offset0:136 offset1:152
	ds_write2_b32 v173, v129, v125 offset0:204 offset1:220
	ds_write2_b32 v173, v118, v114 offset0:32 offset1:48
	ds_write2_b32 v173, v119, v115 offset0:100 offset1:116
	ds_write2_b32 v173, v120, v116 offset0:168 offset1:184
	ds_write2_b32 v173, v121, v117 offset0:236 offset1:252
	ds_write2_b32 v174, v98, v90 offset0:64 offset1:80
	ds_write2_b32 v174, v99, v91 offset0:132 offset1:148
	ds_write2_b32 v174, v100, v92 offset0:200 offset1:216
	ds_write2_b32 v175, v101, v93 offset0:12 offset1:28
	ds_write2_b32 v174, v86, v82 offset0:96 offset1:112
	ds_write2_b32 v174, v87, v83 offset0:164 offset1:180
	ds_write2_b32 v174, v88, v84 offset0:232 offset1:248
	ds_write2_b32 v175, v89, v85 offset0:44 offset1:60
	ds_write2_b32 v176, v66, v58 offset0:128 offset1:144
	ds_write2_b32 v176, v67, v59 offset0:196 offset1:212
	ds_write2_b32 v177, v68, v60 offset0:8 offset1:24
	ds_write2_b32 v177, v69, v61 offset0:76 offset1:92
	ds_write2_b32 v176, v54, v50 offset0:160 offset1:176
	ds_write2_b32 v176, v55, v51 offset0:228 offset1:244
	ds_write2_b32 v177, v56, v52 offset0:40 offset1:56
	ds_write2_b32 v177, v57, v53 offset0:108 offset1:124
	ds_write2_b32 v179, v34, v26 offset0:192 offset1:208
	ds_write2_b32 v178, v35, v27 offset0:4 offset1:20
	ds_write2_b32 v178, v36, v28 offset0:72 offset1:88
	ds_write2_b32 v178, v37, v29 offset0:140 offset1:156
	ds_write2_b32 v179, v22, v18 offset0:224 offset1:240
	ds_write2_b32 v178, v23, v19 offset0:36 offset1:52
	ds_write2_b32 v178, v24, v20 offset0:104 offset1:120
	ds_write2_b32 v178, v25, v21 offset0:172 offset1:188
	s_cbranch_scc1 .LBB0_679
	s_cmpk_gt_u32 s19, 0x3ff
	s_mov_b64 s[30:31], -1
	s_cbranch_scc0 .LBB0_693
	s_cmpk_gt_u32 s19, 0x5ff
	s_mov_b64 s[28:29], -1
	s_cbranch_scc0 .LBB0_689
	s_cmpk_gt_u32 s19, 0x7ff
	s_cbranch_scc0 .LBB0_686
	s_movk_i32 s20, 0x87f
	v_cmp_lt_u32_e32 vcc, s20, v164
	s_and_saveexec_b64 s[28:29], vcc
	s_xor_b64 s[28:29], exec, s[28:29]
	s_cbranch_execz .LBB0_683
	s_mov_b64 s[22:23], -1
	s_cmpk_gt_u32 s19, 0x8ff
	s_mov_b64 s[20:21], -1
	s_cbranch_scc0 .LBB0_676
	s_cmpk_gt_u32 s19, 0xaff
	s_cbranch_scc0 .LBB0_674
	s_movk_i32 s20, 0xb7f
	v_cmp_lt_u32_e32 vcc, s20, v164
	s_and_saveexec_b64 s[20:21], vcc
	s_xor_b64 s[20:21], exec, s[20:21]
	v_add_u32_e32 v130, 0xfffff480, v164
	s_or_saveexec_b64 s[26:27], s[20:21]
	s_mov_b64 s[20:21], 0
	s_mov_b64 s[24:25], 0
	s_xor_b64 exec, exec, s[26:27]
	s_mov_b64 s[24:25], exec
	v_add_u32_e32 v130, 0xfffff500, v164
	s_or_b64 exec, exec, s[26:27]
